# sample out-proj units permuted so each XCD works on one K quarter (A slices shared by 4, B by 2 workgroups per L2)
# speedup vs baseline: 1.0379x; 1.0055x over previous
.LBB0_145:
	v_writelane_b32 v252, s56, 34
	s_nop 1
	v_writelane_b32 v252, s57, 35
	s_or_b64 exec, exec, s[0:1]
	s_add_u32 s80, s10, 0xec00000
	s_addc_u32 s81, s11, 0
	s_add_u32 s25, s10, 0x3800000
	s_addc_u32 s26, s11, 0
	s_add_u32 s0, s10, 0x5a00000
	s_addc_u32 s1, s11, 0
	s_add_u32 s4, s10, 0x400000
	v_writelane_b32 v252, s4, 36
	s_addc_u32 s4, s11, 0
	s_cmpk_lt_i32 s2, 0x400
	v_writelane_b32 v252, s4, 37
	s_cselect_b64 s[4:5], -1, 0
	v_writelane_b32 v252, s4, 38
	s_ashr_i32 s33, s2, 31
	s_ashr_i32 s13, s96, 31
	v_writelane_b32 v252, s5, 39
	s_lshr_b32 s4, s33, 29
	s_add_i32 s5, s2, s4
	s_ashr_i32 s4, s5, 3
	s_and_b32 s5, s5, -8
	s_sub_i32 s6, s2, s5
	s_lshl_b32 s7, s6, 7
	s_and_b32 s5, s1, 0xffff
	s_add_u32 s14, s10, 0xf000200
	s_addc_u32 s15, s11, 0
	s_add_u32 s62, s10, 0xf000400
	s_addc_u32 s63, s11, 0
	s_add_u32 s28, s10, 0xf000500
	v_writelane_b32 v252, s14, 40
	s_addc_u32 s29, s11, 0
	v_lshl_add_u64 v[0:1], v[0:1], 2, s[52:53]
	v_writelane_b32 v252, s15, 41
	s_add_u32 s14, s10, 0xf000600
	s_addc_u32 s15, s11, 0
	v_writelane_b32 v252, s14, 42
	s_mov_b32 s69, 0
	s_mul_i32 s97, s97, s96
	v_writelane_b32 v252, s15, 43
	s_add_u32 s14, s10, 0xf000700
	s_addc_u32 s15, s11, 0
	v_writelane_b32 v252, s14, 44
	s_mul_i32 s97, s97, s54
	s_mov_b32 s83, 0x20000
	v_writelane_b32 v252, s15, 45
	s_add_u32 s14, s10, 0xf000800
	s_addc_u32 s15, s11, 0
	v_writelane_b32 v252, s14, 46
	s_mov_b32 s82, 0x7ffffff0
	v_mov_b32_e32 v161, 0
	v_writelane_b32 v252, s15, 47
	s_add_u32 s14, s10, 0xf000900
	s_addc_u32 s15, s11, 0
	v_writelane_b32 v252, s14, 48
	v_mov_b32_e32 v228, 1
	v_mov_b32_e32 v229, 0x358637bd
	v_writelane_b32 v252, s15, 49
	s_add_u32 s14, s10, 0xf000a00
	s_addc_u32 s15, s11, 0
	v_writelane_b32 v252, s14, 50
	v_mov_b32_e32 v230, 0xec00000
	v_mov_b32_e32 v231, 0xc0
	v_writelane_b32 v252, s15, 51
	s_add_u32 s14, s10, 0xf000b00
	s_addc_u32 s15, s11, 0
	v_writelane_b32 v252, s14, 52
	s_mov_b64 s[76:77], 0x80
	s_nop 0
	v_writelane_b32 v252, s15, 53
	s_add_u32 s14, s10, 0xf000c00
	s_addc_u32 s15, s11, 0
	v_writelane_b32 v252, s14, 54
	s_barrier
	s_nop 0
	v_writelane_b32 v252, s15, 55
	s_add_u32 s14, s10, 0xf000d00
	s_addc_u32 s15, s11, 0
	v_writelane_b32 v252, s14, 56
	s_nop 1
	v_writelane_b32 v252, s15, 57
	s_add_u32 s14, s10, 0xf000e00
	s_addc_u32 s15, s11, 0
	v_writelane_b32 v252, s14, 58
	s_nop 1
	v_writelane_b32 v252, s15, 59
	s_add_u32 s14, s10, 0xf000f00
	s_addc_u32 s15, s11, 0
	v_writelane_b32 v252, s14, 60
	s_nop 1
	v_writelane_b32 v252, s15, 61
	s_add_u32 s14, s10, 0xf001000
	s_addc_u32 s15, s11, 0
	s_add_u32 s86, s10, 0xf001100
	s_addc_u32 s87, s11, 0
	s_add_u32 s74, s10, 0xf001200
	s_addc_u32 s75, s11, 0
	s_add_u32 s78, s10, 0xf001300
	s_addc_u32 s79, s11, 0
	v_writelane_b32 v252, s14, 62
	s_cmp_eq_u32 s12, 15
	s_nop 0
	v_writelane_b32 v252, s15, 63
	s_cselect_b64 s[14:15], -1, 0
	v_writelane_b32 v253, s14, 0
	s_cmp_eq_u32 s12, 14
	s_nop 0
	v_writelane_b32 v253, s15, 1
	s_cselect_b64 s[14:15], -1, 0
	v_writelane_b32 v253, s14, 2
	s_cmp_eq_u32 s12, 13
	s_nop 0
	v_writelane_b32 v253, s15, 3
	s_cselect_b64 s[14:15], -1, 0
	v_writelane_b32 v253, s14, 4
	s_cmp_eq_u32 s12, 12
	s_nop 0
	v_writelane_b32 v253, s15, 5
	s_cselect_b64 s[14:15], -1, 0
	v_writelane_b32 v253, s14, 6
	s_cmp_eq_u32 s12, 11
	s_nop 0
	v_writelane_b32 v253, s15, 7
	s_cselect_b64 s[14:15], -1, 0
	v_writelane_b32 v253, s14, 8
	s_cmp_eq_u32 s12, 10
	s_nop 0
	v_writelane_b32 v253, s15, 9
	s_cselect_b64 s[14:15], -1, 0
	v_writelane_b32 v253, s14, 10
	s_cmp_eq_u32 s12, 9
	s_nop 0
	v_writelane_b32 v253, s15, 11
	s_cselect_b64 s[14:15], -1, 0
	v_writelane_b32 v253, s14, 12
	s_cmp_eq_u32 s12, 8
	s_nop 0
	v_writelane_b32 v253, s15, 13
	s_cselect_b64 s[14:15], -1, 0
	v_writelane_b32 v253, s14, 14
	s_cmp_eq_u32 s12, 7
	s_nop 0
	v_writelane_b32 v253, s15, 15
	s_mov_b64 s[14:15], 0x1400
	v_lshl_add_u64 v[218:219], v[0:1], 0, s[14:15]
	s_mov_b64 s[14:15], 0x2400
	v_lshl_add_u64 v[220:221], v[0:1], 0, s[14:15]
	s_cselect_b64 s[14:15], -1, 0
	v_writelane_b32 v253, s14, 16
	s_cmp_eq_u32 s12, 6
	s_nop 0
	v_writelane_b32 v253, s15, 17
	s_cselect_b64 s[14:15], -1, 0
	v_writelane_b32 v253, s14, 18
	s_cmp_eq_u32 s12, 5
	s_nop 0
	v_writelane_b32 v253, s15, 19
	s_cselect_b64 s[14:15], -1, 0
	v_writelane_b32 v253, s14, 20
	s_cmp_eq_u32 s12, 4
	s_nop 0
	v_writelane_b32 v253, s15, 21
	s_cselect_b64 s[14:15], -1, 0
	v_writelane_b32 v253, s14, 22
	s_cmp_eq_u32 s12, 3
	s_nop 0
	v_writelane_b32 v253, s15, 23
	s_cselect_b64 s[14:15], -1, 0
	v_writelane_b32 v253, s14, 24
	s_cmp_eq_u32 s12, 2
	s_nop 0
	v_writelane_b32 v253, s15, 25
	s_cselect_b64 s[14:15], -1, 0
	v_writelane_b32 v253, s14, 26
	s_cmp_eq_u32 s12, 1
	s_nop 0
	v_writelane_b32 v253, s15, 27
	s_cselect_b64 s[14:15], -1, 0
	v_writelane_b32 v253, s14, 28
	s_cmp_eq_u32 s12, 0
	s_nop 0
	v_writelane_b32 v253, s15, 29
	s_cselect_b64 s[14:15], -1, 0
	v_writelane_b32 v253, s14, 30
	s_nop 1
	v_writelane_b32 v253, s15, 31
	s_add_u32 s14, s10, 0xf003400
	s_addc_u32 s15, s11, 0
	v_writelane_b32 v253, s14, 32
	s_nop 1
	v_writelane_b32 v253, s15, 33
	s_add_u32 s14, s10, 0xf003500
	s_addc_u32 s15, s11, 0
	v_writelane_b32 v253, s14, 34
	s_add_u32 s12, s10, 0xef00000
	s_nop 0
	v_writelane_b32 v253, s15, 35
	v_writelane_b32 v253, s12, 36
	s_addc_u32 s12, s11, 0
	s_cmp_gt_i32 s2, 63
	v_writelane_b32 v253, s12, 37
	s_cselect_b64 s[14:15], -1, 0
	v_writelane_b32 v253, s14, 38
	s_add_i32 s12, s2, 0xffffff80
	s_nop 0
	v_writelane_b32 v253, s15, 39
	v_writelane_b32 v253, s12, 40
	s_sub_i32 s14, s2, 64
	s_add_i32 s12, s2, 0x80
	s_cmp_lt_u32 s55, 64
	v_writelane_b32 v253, s12, 41
	s_cselect_b64 s[16:17], -1, 0
	v_writelane_b32 v253, s16, 42
	v_readlane_b32 s12, v252, 32
	s_lshl_b32 s15, s12, 4
	v_writelane_b32 v253, s17, 43
	s_lshl_b32 s34, s12, 5
	s_add_i32 s12, s3, 0x1000
	v_writelane_b32 v253, s15, 44
	s_add_u32 s16, s10, 0x3600000
	v_writelane_b32 v253, s12, 45
	s_addc_u32 s17, s11, 0
	v_writelane_b32 v253, s16, 46
	s_nop 1
	v_writelane_b32 v253, s17, 47
	s_add_u32 s16, s10, 0x3700000
	s_addc_u32 s17, s11, 0
	v_writelane_b32 v253, s16, 48
	s_nop 1
	v_writelane_b32 v253, s17, 49
	s_add_u32 s16, s10, 0x3400000
	s_addc_u32 s17, s11, 0
	v_writelane_b32 v253, s16, 50
	s_add_u32 s12, s10, 0x5800000
	s_nop 0
	v_writelane_b32 v253, s17, 51
	v_writelane_b32 v253, s12, 52
	s_addc_u32 s12, s11, 0
	s_add_u32 s88, s10, 0xda00000
	s_addc_u32 s20, s11, 0
	s_add_u32 s16, s10, 0xec10000
	v_writelane_b32 v253, s12, 53
	s_addc_u32 s17, s11, 0
	v_writelane_b32 v253, s16, 54
	s_and_b32 s89, s20, 0xffff
	s_cmpk_lt_u32 s14, 0xa0
	v_writelane_b32 v253, s17, 55
	v_writelane_b32 v253, s14, 56
	s_cselect_b64 s[14:15], -1, 0
	s_add_i32 s12, s2, 0xffffff60
	v_writelane_b32 v253, s14, 57
	s_cmp_lt_i32 s2, 64
	s_cselect_b32 s12, s2, s12
	v_writelane_b32 v253, s15, 58
	s_add_u32 s14, s8, 0x6460000
	v_writelane_b32 v253, s12, 59
	s_addc_u32 s15, s9, 0
	v_writelane_b32 v253, s14, 60
	s_nop 1
	v_writelane_b32 v253, s15, 61
	s_add_u32 s14, s8, 0x4660000
	s_addc_u32 s15, s9, 0
	v_writelane_b32 v253, s14, 62
	s_nop 1
	v_writelane_b32 v253, s15, 63
	s_add_u32 s14, s8, 0x45e0000
	s_addc_u32 s15, s9, 0
	v_writelane_b32 v254, s14, 0
	s_nop 1
	v_writelane_b32 v254, s15, 1
	s_add_u32 s14, s8, 0x4400000
	s_addc_u32 s15, s9, 0
	s_add_u32 s35, s10, 0x5a01000
	v_writelane_b32 v254, s14, 2
	s_addc_u32 s36, s11, 0
	s_add_u32 s12, s10, 0x2400000
	v_writelane_b32 v254, s15, 3
	v_writelane_b32 v254, s12, 4
	s_addc_u32 s12, s11, 0
	s_cmpk_lt_i32 s2, 0x100
	v_writelane_b32 v254, s12, 5
	s_cselect_b64 s[14:15], -1, 0
	s_lshl_b32 s12, s6, 5
	s_add_u32 s19, s10, 0xda01000
	s_addc_u32 s21, s11, 0
	s_add_u32 s22, s10, 0xe400000
	s_addc_u32 s23, s11, 0
	v_writelane_b32 v254, s14, 6
	s_cmp_lt_i32 s2, 16
	s_nop 0
	v_writelane_b32 v254, s15, 7
	s_cselect_b64 s[14:15], -1, 0
	v_writelane_b32 v254, s14, 8
	s_lshl_b32 s38, s96, 4
	s_lshl_b32 s18, s6, 1
	v_writelane_b32 v254, s15, 9
	s_and_b32 s98, s2, 6
	s_lshl_b32 s98, s98, 3
	s_bfe_u32 s99, s2, 0x10005
	s_lshl_b32 s99, s99, 3
	s_or_b32 s98, s98, s99
	s_bfe_u32 s99, s2, 0x20003
	s_lshl_b32 s99, s99, 1
	s_or_b32 s98, s98, s99
	s_and_b32 s99, s2, 1
	s_or_b32 s98, s98, s99
	s_cmpk_lt_u32 s2, 0x40
	s_cselect_b32 s98, s98, s2
	s_lshr_b32 s14, s33, 28
	s_add_i32 s16, s98, s14
	s_ashr_i32 s17, s16, 4
	s_lshl_b32 s14, s17, 9
	s_ashr_i32 s15, s14, 31
	v_writelane_b32 v254, s19, 10
	s_lshl_b64 s[14:15], s[14:15], 1
	s_add_i32 s40, s38, 0xfffffc00
	v_writelane_b32 v254, s21, 11
	s_add_u32 s37, s19, s14
	v_writelane_b32 v254, s14, 12
	s_addc_u32 s39, s21, s15
	s_add_i32 s68, s17, -2
	v_writelane_b32 v254, s15, 13
	s_and_b32 s14, s16, -16
	s_sub_i32 s24, s98, s14
	s_lshl_b64 s[14:15], s[68:69], 21
	s_add_u32 s16, s22, s14
	v_writelane_b32 v254, s22, 14
	s_addc_u32 s17, s23, s15
	s_add_i32 s14, s98, 15
	s_cmp_lt_u32 s14, 31
	s_cselect_b32 s14, 0, 0x800
	v_writelane_b32 v254, s23, 15
	s_add_u32 s19, s88, s14
	v_writelane_b32 v254, s20, 16
	s_addc_u32 s20, s20, 0
	s_bfe_i32 s14, s24, 0x80000
	s_bfe_u32 s14, s14, 0x3000c
	s_add_i32 s14, s24, s14
	s_bfe_i32 s15, s14, 0x80000
	s_and_b32 s14, s14, 0xfff8
	s_sext_i32_i16 s15, s15
	s_sub_i32 s14, s24, s14
	s_ashr_i32 s15, s15, 3
	s_bfe_i32 s21, s14, 0x80000
	s_lshl_b32 s22, s14, 1
	v_writelane_b32 v254, s24, 17
	s_ashr_i32 s23, s24, 31
	v_writelane_b32 v254, s23, 18
	s_cmp_lt_i32 s6, 0
	s_mul_i32 s23, s6, 0x81
	s_cselect_b32 s7, s23, s7
	s_mul_i32 s23, s6, 33
	s_mul_i32 s6, s6, 3
	s_cselect_b32 s12, s23, s12
	s_cselect_b32 s18, s6, s18
	s_add_i32 s6, s7, s4
	s_ashr_i32 s7, s6, 31
	s_lshr_b32 s7, s7, 25
	s_add_i32 s7, s6, s7
	s_and_b32 s23, s7, 0xff80
	s_sub_i32 s6, s6, s23
	s_bfe_i32 s23, s6, 0x80000
	s_bfe_u32 s23, s23, 0x3000c
	s_add_i32 s23, s6, s23
	s_and_b32 s24, s23, 0xf8
	s_sub_i32 s6, s6, s24
	s_ashr_i32 s7, s7, 7
	s_bfe_i32 s23, s23, 0x80000
	s_lshl_b32 s7, s7, 3
	s_sext_i32_i16 s23, s23
	s_sext_i32_i8 s6, s6
	s_add_i32 s42, s7, s6
	s_ashr_i32 s6, s23, 3
	v_writelane_b32 v254, s6, 19
	s_lshr_b32 s6, s23, 3
	s_bfe_i64 s[6:7], s[6:7], 0x100000
	s_lshl_b64 s[6:7], s[6:7], 19
	v_writelane_b32 v254, s6, 20
	s_ashr_i32 s43, s42, 31
	s_mul_i32 s14, s14, 3
	v_writelane_b32 v254, s7, 21
	s_mov_b32 s6, s42
	v_writelane_b32 v254, s6, 22
	s_nop 1
	v_writelane_b32 v254, s7, 23
	s_lshl_b64 s[6:7], s[42:43], 19
	v_writelane_b32 v254, s25, 24
	s_add_u32 s6, s25, s6
	v_writelane_b32 v254, s26, 25
	s_addc_u32 s7, s26, s7
	s_add_u32 s24, s6, 0x40000
	v_writelane_b32 v254, s6, 26
	s_addc_u32 s25, s7, 0
	s_mov_b64 s[26:27], s[28:29]
	v_writelane_b32 v254, s7, 27
	s_add_i32 s6, s12, s4
	s_ashr_i32 s7, s6, 31
	s_lshr_b32 s7, s7, 27
	s_add_i32 s7, s6, s7
	s_and_b32 s12, s7, 0xffe0
	s_sub_i32 s6, s6, s12
	s_bfe_i32 s12, s6, 0x80000
	s_bfe_u32 s12, s12, 0x3000c
	s_add_i32 s12, s6, s12
	s_and_b32 s23, s12, 0xf8
	s_sub_i32 s6, s6, s23
	s_ashr_i32 s7, s7, 5
	s_bfe_i32 s12, s12, 0x80000
	v_writelane_b32 v254, s24, 28
	s_lshl_b32 s7, s7, 3
	s_sext_i32_i16 s12, s12
	s_sext_i32_i8 s6, s6
	v_writelane_b32 v254, s25, 29
	s_add_i32 s24, s7, s6
	s_ashr_i32 s6, s12, 3
	v_writelane_b32 v254, s6, 30
	s_lshr_b32 s6, s12, 3
	s_bfe_i64 s[6:7], s[6:7], 0x100000
	s_lshl_b64 s[6:7], s[6:7], 20
	v_writelane_b32 v254, s6, 31
	s_ashr_i32 s25, s24, 31
	s_mov_b32 s28, s69
	v_writelane_b32 v254, s7, 32
	s_mov_b32 s6, s24
	v_writelane_b32 v254, s6, 33
	s_nop 1
	v_writelane_b32 v254, s7, 34
	s_lshl_b64 s[6:7], s[24:25], 21
	s_add_u32 s6, s35, s6
	v_writelane_b32 v254, s35, 35
	s_addc_u32 s7, s36, s7
	v_writelane_b32 v254, s36, 36
	s_add_u32 s24, s6, 0x100000
	v_writelane_b32 v254, s6, 37
	s_addc_u32 s25, s7, 0
	s_add_i32 s4, s18, s4
	v_writelane_b32 v254, s7, 38
	s_ashr_i32 s6, s4, 31
	s_lshr_b32 s6, s6, 27
	s_add_i32 s6, s4, s6
	s_and_b32 s7, s6, 0xffffffe0
	s_ashr_i32 s6, s6, 5
	s_sub_i32 s23, s4, s7
	s_sext_i32_i16 s4, s21
	s_lshl_b32 s21, s6, 3
	v_writelane_b32 v254, s24, 39
	s_sub_i32 s6, 4, s21
	v_cvt_f32_i32_e32 v0, s23
	v_writelane_b32 v254, s25, 40
	s_min_u32 s24, s6, 8
	s_cmp_lt_i32 s4, 0
	s_cselect_b32 s4, s14, s22
	s_add_i32 s4, s4, s15
	s_bfe_i32 s6, s4, 0x80000
	s_bfe_u32 s6, s6, 0x2000d
	s_add_i32 s6, s4, s6
	s_bfe_i32 s7, s6, 0x80000
	s_sext_i32_i16 s12, s7
	s_and_b32 s6, s6, 0xfffc
	s_ashr_i32 s14, s12, 2
	s_lshr_b32 s12, s12, 2
	s_sub_i32 s4, s4, s6
	v_writelane_b32 v254, s14, 41
	s_bfe_i64 s[14:15], s[12:13], 0x100000
	s_bfe_i64 s[6:7], s[4:5], 0x80000
	s_lshl_b64 s[14:15], s[14:15], 20
	s_lshl_b64 s[6:7], s[6:7], 21
	v_writelane_b32 v254, s14, 42
	s_add_u32 s6, s37, s6
	s_addc_u32 s7, s39, s7
	v_writelane_b32 v254, s15, 43
	v_writelane_b32 v254, s37, 44
	v_writelane_b32 v254, s39, 45
	s_add_u32 s14, s6, 0x100000
	v_cvt_f32_ubyte0_e32 v1, s24
	v_writelane_b32 v254, s6, 46
	s_addc_u32 s15, s7, 0
	v_rcp_iflag_f32_e32 v2, v1
	s_cmp_lt_i32 s98, 32
	v_writelane_b32 v254, s7, 47
	s_cselect_b32 s6, s20, s17
	s_movk_i32 s7, 0x1000
	v_writelane_b32 v254, s14, 48
	s_cselect_b32 s12, s7, 0x400
	s_cselect_b32 s18, 13, 11
	s_cselect_b32 s92, s19, s16
	s_and_b32 s93, s6, 0xffff
	s_ashr_i32 s6, s23, 30
	v_writelane_b32 v254, s15, 49
	s_or_b32 s14, s6, 1
	v_mul_f32_e32 v2, v0, v2
	s_lshl_b32 s6, s12, 5
	v_trunc_f32_e32 v2, v2
	v_writelane_b32 v254, s6, 50
	v_fma_f32 v0, -v2, v1, v0
	v_writelane_b32 v254, s34, 51
	s_add_i32 s6, s34, 0
	v_writelane_b32 v254, s6, 52
	v_cmp_ge_f32_e64 s[6:7], |v0|, v1
	v_cvt_i32_f32_e32 v0, v2
	s_and_b64 s[6:7], s[6:7], exec
	s_sext_i32_i8 s4, s4
	v_writelane_b32 v254, s4, 53
	s_cselect_b32 s4, s14, 0
	v_readfirstlane_b32 s6, v0
	s_add_i32 s6, s6, s4
	s_mul_i32 s4, s6, s24
	s_sub_i32 s7, s23, s4
	s_sext_i32_i8 s7, s7
	s_add_i32 s14, s21, s7
	s_sext_i32_i8 s7, s6
	v_writelane_b32 v254, s7, 54
	s_bfe_i64 s[6:7], s[6:7], 0x80000
	s_lshl_b64 s[6:7], s[6:7], 20
	v_writelane_b32 v254, s6, 55
	s_ashr_i32 s15, s14, 31
	s_mov_b32 s4, s0
	v_writelane_b32 v254, s7, 56
	s_mul_i32 s6, s12, 0xc0
	v_writelane_b32 v254, s6, 57
	s_mov_b32 s6, s14
	v_writelane_b32 v254, s6, 58
	s_mov_b32 s12, 0xbfb8aa3b
	s_nop 0
	v_writelane_b32 v254, s7, 59
	s_lshl_b64 s[6:7], s[14:15], 21
	v_writelane_b32 v254, s6, 60
	s_mov_b64 s[14:15], 0xffffffff
	s_nop 0
	v_writelane_b32 v254, s7, 61
	s_add_u32 s6, s10, 0x5840080
	v_writelane_b32 v254, s6, 62
	s_addc_u32 s6, s11, 0
	v_writelane_b32 v254, s6, 63
	s_add_u32 s6, s10, 0x400100
	v_writelane_b32 v255, s6, 0
	s_addc_u32 s6, s11, 0
	s_ashr_i32 s39, s38, 31
	v_writelane_b32 v255, s6, 1
	s_add_i32 s6, s3, 0xfffbf800
	s_lshl_b64 s[70:71], s[38:39], 2
	v_writelane_b32 v255, s6, 2
	s_add_u32 s6, s8, 0x1000
	v_writelane_b32 v255, s6, 3
	s_addc_u32 s6, s9, 0
	v_writelane_b32 v255, s6, 4
	s_lshl_b32 s6, s2, 4
	s_addk_i32 s6, 0x3c00
	v_writelane_b32 v255, s6, 5
	s_add_i32 s6, 0, 0x20004
	v_writelane_b32 v255, s6, 6
	s_lshl_b64 s[6:7], s[38:39], 12
	v_writelane_b32 v255, s6, 7
	s_ashr_i32 s41, s40, 31
	s_lshl_b64 s[84:85], s[38:39], 11
	v_writelane_b32 v255, s7, 8
	s_mov_b32 s6, s38
	v_writelane_b32 v255, s6, 9
	s_nop 1
	v_writelane_b32 v255, s7, 10
	s_lshl_b64 s[6:7], s[38:39], 13
	v_writelane_b32 v255, s6, 11
	s_nop 1
	v_writelane_b32 v255, s7, 12
	s_lshl_b64 s[6:7], s[40:41], 2
	v_writelane_b32 v255, s6, 13
	s_nop 1
	v_writelane_b32 v255, s7, 14
	s_lshl_b64 s[6:7], s[40:41], 12
	v_writelane_b32 v255, s6, 15
	s_nop 1
	v_writelane_b32 v255, s7, 16
	s_lshl_b64 s[6:7], s[40:41], 11
	v_writelane_b32 v255, s6, 17
	s_nop 1
	v_writelane_b32 v255, s7, 18
	s_mov_b32 s6, s40
	v_writelane_b32 v255, s6, 19
	s_nop 1
	v_writelane_b32 v255, s7, 20
	s_lshl_b64 s[6:7], s[40:41], 13
	v_writelane_b32 v255, s6, 21
	s_nop 1
	v_writelane_b32 v255, s7, 22
	v_writelane_b32 v255, s62, 23
	s_nop 1
	v_writelane_b32 v255, s63, 24
	v_writelane_b32 v255, s26, 25
	s_nop 1
	v_writelane_b32 v255, s27, 26
	v_writelane_b32 v255, s80, 27
	s_nop 1
	v_writelane_b32 v255, s81, 28
	s_branch .LBB0_149
